# hot loop heads (GEMM K loops, attention tile loop and PV block, dwconv pass loop) aligned to 64 bytes with s_nop padding
# baseline (speedup 1.0000x reference)
.LBB0_125:
	s_ashr_i32 s9, s8, 31
	s_lshl_b64 s[22:23], s[8:9], 19
	s_add_u32 s40, s42, s22
	s_addc_u32 s41, s43, s23
	s_and_b64 s[22:23], s[38:39], exec
	s_cselect_b32 s9, s41, s11
	s_cselect_b32 s22, s40, s10
	s_ashr_i32 s7, s6, 31
	s_lshl_b64 s[24:25], s[6:7], 19
	s_add_u32 s82, s19, s24
	s_addc_u32 s83, s50, s25
	s_and_b64 s[24:25], s[38:39], exec
	s_cselect_b32 s7, s83, s37
	s_cselect_b32 s23, s82, s36
	s_add_u32 s10, s10, 0x40080
	s_addc_u32 s11, s11, 0
	s_add_u32 s24, s36, 0x100
	s_addc_u32 s25, s37, 0
	s_mov_b32 s26, -2
	s_add_u32 s13, s10, 0xfffc0080
	s_addc_u32 s27, s11, -1
	s_add_i32 s28, 0, 0x10000
	s_cmp_eq_u32 s26, 12
	s_cselect_b32 s49, s9, s27
	s_cselect_b32 s48, s22, s13
	v_add_u32_e32 v0, s28, v150
	s_cselect_b32 s37, s7, s25
	s_cselect_b32 s36, s23, s24
	s_add_i32 s13, 0, 0x14000
	ds_read_b128 v[166:169], v0
	ds_read_b128 v[170:173], v0 offset:1024
	ds_read_b128 v[174:177], v0 offset:2048
	ds_read_b128 v[178:181], v0 offset:3072
	v_add_u32_e32 v0, s13, v150
	ds_read_b128 v[182:185], v0
	ds_read_b128 v[186:189], v0 offset:1024
	ds_read_b128 v[190:193], v0 offset:2048
	ds_read_b128 v[194:197], v0 offset:3072
	v_lshl_add_u64 v[130:131], s[10:11], 0, v[146:147]
	s_add_i32 m0, s52, 0xc000
	ds_read_b128 v[198:201], v152
	ds_read_b128 v[202:205], v152 offset:1024
	ds_read_b128 v[206:209], v152 offset:2048
	ds_read_b128 v[210:213], v152 offset:3072
	ds_read_b128 v[214:217], v152 offset:4096
	ds_read_b128 v[218:221], v152 offset:5120
	ds_read_b128 v[222:225], v152 offset:6144
	ds_read_b128 v[226:229], v152 offset:7168
	global_load_lds_dwordx4 v[130:131], off
	v_lshl_add_u64 v[130:131], s[10:11], 0, v[148:149]
	s_add_i32 m0, s52, 0xe000
	s_nop 0
	global_load_lds_dwordx4 v[130:131], off
	s_waitcnt vmcnt(8)
	s_waitcnt lgkmcnt(0)
	s_barrier
	s_waitcnt lgkmcnt(0)
	v_mfma_f32_16x16x32_bf16 v[126:129], v[166:169], v[198:201], 0
	v_mfma_f32_16x16x32_bf16 v[114:117], v[174:177], v[198:201], 0
	v_mfma_f32_16x16x32_bf16 v[110:113], v[166:169], v[206:209], 0
	v_mfma_f32_16x16x32_bf16 v[98:101], v[174:177], v[206:209], 0
	v_mfma_f32_16x16x32_bf16 v[94:97], v[166:169], v[214:217], 0
	v_mfma_f32_16x16x32_bf16 v[82:85], v[174:177], v[214:217], 0
	v_mfma_f32_16x16x32_bf16 v[78:81], v[166:169], v[222:225], 0
	v_mfma_f32_16x16x32_bf16 v[66:69], v[174:177], v[222:225], 0
	v_mfma_f32_16x16x32_bf16 v[126:129], v[170:173], v[202:205], v[126:129]
	v_mfma_f32_16x16x32_bf16 v[114:117], v[178:181], v[202:205], v[114:117]
	v_mfma_f32_16x16x32_bf16 v[110:113], v[170:173], v[210:213], v[110:113]
	v_mfma_f32_16x16x32_bf16 v[98:101], v[178:181], v[210:213], v[98:101]
	v_mfma_f32_16x16x32_bf16 v[94:97], v[170:173], v[218:221], v[94:97]
	v_mfma_f32_16x16x32_bf16 v[82:85], v[178:181], v[218:221], v[82:85]
	v_mfma_f32_16x16x32_bf16 v[78:81], v[170:173], v[226:229], v[78:81]
	v_mfma_f32_16x16x32_bf16 v[66:69], v[178:181], v[226:229], v[66:69]
	v_mfma_f32_16x16x32_bf16 v[122:125], v[182:185], v[198:201], 0
	v_mfma_f32_16x16x32_bf16 v[118:121], v[190:193], v[198:201], 0
	v_mfma_f32_16x16x32_bf16 v[106:109], v[182:185], v[206:209], 0
	v_mfma_f32_16x16x32_bf16 v[102:105], v[190:193], v[206:209], 0
	v_mfma_f32_16x16x32_bf16 v[90:93], v[182:185], v[214:217], 0
	v_mfma_f32_16x16x32_bf16 v[86:89], v[190:193], v[214:217], 0
	v_mfma_f32_16x16x32_bf16 v[74:77], v[182:185], v[222:225], 0
	v_mfma_f32_16x16x32_bf16 v[70:73], v[190:193], v[222:225], 0
	v_mfma_f32_16x16x32_bf16 v[122:125], v[186:189], v[202:205], v[122:125]
	v_mfma_f32_16x16x32_bf16 v[118:121], v[194:197], v[202:205], v[118:121]
	v_mfma_f32_16x16x32_bf16 v[106:109], v[186:189], v[210:213], v[106:109]
	v_mfma_f32_16x16x32_bf16 v[102:105], v[194:197], v[210:213], v[102:105]
	v_mfma_f32_16x16x32_bf16 v[90:93], v[186:189], v[218:221], v[90:93]
	v_mfma_f32_16x16x32_bf16 v[86:89], v[194:197], v[218:221], v[86:89]
	v_mfma_f32_16x16x32_bf16 v[74:77], v[186:189], v[226:229], v[74:77]
	v_mfma_f32_16x16x32_bf16 v[70:73], v[194:197], v[226:229], v[70:73]
	s_barrier
	s_add_i32 s27, s28, s51
	v_lshl_add_u64 v[130:131], s[36:37], 0, v[142:143]
	s_mov_b32 m0, s27
	ds_read_b128 v[198:201], v152 offset:16384
	ds_read_b128 v[202:205], v152 offset:17408
	ds_read_b128 v[206:209], v152 offset:18432
	ds_read_b128 v[210:213], v152 offset:19456
	ds_read_b128 v[214:217], v152 offset:20480
	ds_read_b128 v[218:221], v152 offset:21504
	ds_read_b128 v[222:225], v152 offset:22528
	ds_read_b128 v[226:229], v152 offset:23552
	global_load_lds_dwordx4 v[130:131], off
	s_add_i32 m0, s27, 0x2000
	s_add_u32 s28, s36, 0x40000
	v_lshl_add_u64 v[136:137], s[36:37], 0, v[138:139]
	s_addc_u32 s29, s37, 0
	s_add_i32 s13, s13, s51
	global_load_lds_dwordx4 v[136:137], off
	v_lshl_add_u64 v[230:231], s[28:29], 0, v[142:143]
	s_mov_b32 m0, s13
	v_lshl_add_u64 v[232:233], s[48:49], 0, v[140:141]
	global_load_lds_dwordx4 v[230:231], off
	v_lshl_add_u64 v[230:231], s[28:29], 0, v[138:139]
	s_add_i32 m0, s13, 0x2000
	s_nop 0
	global_load_lds_dwordx4 v[230:231], off
	v_lshl_add_u64 v[230:231], s[48:49], 0, v[144:145]
	s_mov_b32 m0, s52
	s_nop 0
	global_load_lds_dwordx4 v[230:231], off
	s_mov_b32 m0, s53
	s_nop 0
	global_load_lds_dwordx4 v[232:233], off
	s_waitcnt vmcnt(8)
	s_waitcnt lgkmcnt(0)
	s_barrier
	s_waitcnt lgkmcnt(0)
	v_mfma_f32_16x16x32_bf16 v[62:65], v[166:169], v[198:201], 0
	v_mfma_f32_16x16x32_bf16 v[50:53], v[174:177], v[198:201], 0
	v_mfma_f32_16x16x32_bf16 v[46:49], v[166:169], v[206:209], 0
	v_mfma_f32_16x16x32_bf16 v[34:37], v[174:177], v[206:209], 0
	v_mfma_f32_16x16x32_bf16 v[30:33], v[166:169], v[214:217], 0
	v_mfma_f32_16x16x32_bf16 v[18:21], v[174:177], v[214:217], 0
	v_mfma_f32_16x16x32_bf16 v[14:17], v[166:169], v[222:225], 0
	v_mfma_f32_16x16x32_bf16 v[6:9], v[174:177], v[222:225], 0
	v_mfma_f32_16x16x32_bf16 v[62:65], v[170:173], v[202:205], v[62:65]
	v_mfma_f32_16x16x32_bf16 v[50:53], v[178:181], v[202:205], v[50:53]
	v_mfma_f32_16x16x32_bf16 v[46:49], v[170:173], v[210:213], v[46:49]
	v_mfma_f32_16x16x32_bf16 v[34:37], v[178:181], v[210:213], v[34:37]
	v_mfma_f32_16x16x32_bf16 v[30:33], v[170:173], v[218:221], v[30:33]
	v_mfma_f32_16x16x32_bf16 v[18:21], v[178:181], v[218:221], v[18:21]
	v_mfma_f32_16x16x32_bf16 v[14:17], v[170:173], v[226:229], v[14:17]
	v_mfma_f32_16x16x32_bf16 v[6:9], v[178:181], v[226:229], v[6:9]
	v_mfma_f32_16x16x32_bf16 v[58:61], v[182:185], v[198:201], 0
	v_mfma_f32_16x16x32_bf16 v[54:57], v[190:193], v[198:201], 0
	v_mfma_f32_16x16x32_bf16 v[42:45], v[182:185], v[206:209], 0
	v_mfma_f32_16x16x32_bf16 v[38:41], v[190:193], v[206:209], 0
	v_mfma_f32_16x16x32_bf16 v[26:29], v[182:185], v[214:217], 0
	v_mfma_f32_16x16x32_bf16 v[22:25], v[190:193], v[214:217], 0
	v_mfma_f32_16x16x32_bf16 v[10:13], v[182:185], v[222:225], 0
	v_mfma_f32_16x16x32_bf16 v[2:5], v[190:193], v[222:225], 0
	v_mfma_f32_16x16x32_bf16 v[58:61], v[186:189], v[202:205], v[58:61]
	v_mfma_f32_16x16x32_bf16 v[54:57], v[194:197], v[202:205], v[54:57]
	v_mfma_f32_16x16x32_bf16 v[42:45], v[186:189], v[210:213], v[42:45]
	v_mfma_f32_16x16x32_bf16 v[38:41], v[194:197], v[210:213], v[38:41]
	v_mfma_f32_16x16x32_bf16 v[26:29], v[186:189], v[218:221], v[26:29]
	v_mfma_f32_16x16x32_bf16 v[22:25], v[194:197], v[218:221], v[22:25]
	v_mfma_f32_16x16x32_bf16 v[10:13], v[186:189], v[226:229], v[10:13]
	v_mfma_f32_16x16x32_bf16 v[2:5], v[194:197], v[226:229], v[2:5]
	s_barrier
	s_add_i32 s13, 0, 0x18000
	v_add_u32_e32 v0, s13, v150
	s_add_i32 s27, 0, 0x1c000
	ds_read_b128 v[166:169], v0
	ds_read_b128 v[170:173], v0 offset:1024
	ds_read_b128 v[174:177], v0 offset:2048
	ds_read_b128 v[178:181], v0 offset:3072
	v_add_u32_e32 v0, s27, v150
	ds_read_b128 v[182:185], v0
	ds_read_b128 v[186:189], v0 offset:1024
	ds_read_b128 v[190:193], v0 offset:2048
	ds_read_b128 v[194:197], v0 offset:3072
	s_add_u32 s28, s48, 0x40000
	s_addc_u32 s29, s49, 0
	s_mov_b32 m0, s54
	v_lshl_add_u64 v[234:235], s[28:29], 0, v[144:145]
	ds_read_b128 v[198:201], v152 offset:32768
	ds_read_b128 v[202:205], v152 offset:33792
	ds_read_b128 v[206:209], v152 offset:34816
	ds_read_b128 v[210:213], v152 offset:35840
	ds_read_b128 v[214:217], v152 offset:36864
	ds_read_b128 v[218:221], v152 offset:37888
	ds_read_b128 v[222:225], v152 offset:38912
	ds_read_b128 v[226:229], v152 offset:39936
	global_load_lds_dwordx4 v[234:235], off
	v_lshl_add_u64 v[234:235], s[28:29], 0, v[140:141]
	s_mov_b32 m0, s55
	s_nop 0
	global_load_lds_dwordx4 v[234:235], off
	s_waitcnt vmcnt(8)
	s_waitcnt lgkmcnt(0)
	s_barrier
	s_waitcnt lgkmcnt(0)
	v_mfma_f32_16x16x32_bf16 v[126:129], v[166:169], v[198:201], v[126:129]
	v_mfma_f32_16x16x32_bf16 v[114:117], v[174:177], v[198:201], v[114:117]
	v_mfma_f32_16x16x32_bf16 v[110:113], v[166:169], v[206:209], v[110:113]
	v_mfma_f32_16x16x32_bf16 v[98:101], v[174:177], v[206:209], v[98:101]
	v_mfma_f32_16x16x32_bf16 v[94:97], v[166:169], v[214:217], v[94:97]
	v_mfma_f32_16x16x32_bf16 v[82:85], v[174:177], v[214:217], v[82:85]
	v_mfma_f32_16x16x32_bf16 v[78:81], v[166:169], v[222:225], v[78:81]
	v_mfma_f32_16x16x32_bf16 v[66:69], v[174:177], v[222:225], v[66:69]
	v_mfma_f32_16x16x32_bf16 v[126:129], v[170:173], v[202:205], v[126:129]
	v_mfma_f32_16x16x32_bf16 v[114:117], v[178:181], v[202:205], v[114:117]
	v_mfma_f32_16x16x32_bf16 v[110:113], v[170:173], v[210:213], v[110:113]
	v_mfma_f32_16x16x32_bf16 v[98:101], v[178:181], v[210:213], v[98:101]
	v_mfma_f32_16x16x32_bf16 v[94:97], v[170:173], v[218:221], v[94:97]
	v_mfma_f32_16x16x32_bf16 v[82:85], v[178:181], v[218:221], v[82:85]
	v_mfma_f32_16x16x32_bf16 v[78:81], v[170:173], v[226:229], v[78:81]
	v_mfma_f32_16x16x32_bf16 v[66:69], v[178:181], v[226:229], v[66:69]
	v_mfma_f32_16x16x32_bf16 v[122:125], v[182:185], v[198:201], v[122:125]
	v_mfma_f32_16x16x32_bf16 v[118:121], v[190:193], v[198:201], v[118:121]
	v_mfma_f32_16x16x32_bf16 v[106:109], v[182:185], v[206:209], v[106:109]
	v_mfma_f32_16x16x32_bf16 v[102:105], v[190:193], v[206:209], v[102:105]
	v_mfma_f32_16x16x32_bf16 v[90:93], v[182:185], v[214:217], v[90:93]
	v_mfma_f32_16x16x32_bf16 v[86:89], v[190:193], v[214:217], v[86:89]
	v_mfma_f32_16x16x32_bf16 v[74:77], v[182:185], v[222:225], v[74:77]
	v_mfma_f32_16x16x32_bf16 v[70:73], v[190:193], v[222:225], v[70:73]
	v_mfma_f32_16x16x32_bf16 v[122:125], v[186:189], v[202:205], v[122:125]
	v_mfma_f32_16x16x32_bf16 v[118:121], v[194:197], v[202:205], v[118:121]
	v_mfma_f32_16x16x32_bf16 v[106:109], v[186:189], v[210:213], v[106:109]
	v_mfma_f32_16x16x32_bf16 v[102:105], v[194:197], v[210:213], v[102:105]
	v_mfma_f32_16x16x32_bf16 v[90:93], v[186:189], v[218:221], v[90:93]
	v_mfma_f32_16x16x32_bf16 v[86:89], v[194:197], v[218:221], v[86:89]
	v_mfma_f32_16x16x32_bf16 v[74:77], v[186:189], v[226:229], v[74:77]
	v_mfma_f32_16x16x32_bf16 v[70:73], v[194:197], v[226:229], v[70:73]
	s_barrier
	s_add_i32 s13, s13, s51
	v_lshl_add_u64 v[130:131], v[130:131], 0, s[84:85]
	s_mov_b32 m0, s13
	ds_read_b128 v[198:201], v152 offset:49152
	ds_read_b128 v[202:205], v152 offset:50176
	ds_read_b128 v[206:209], v152 offset:51200
	ds_read_b128 v[210:213], v152 offset:52224
	ds_read_b128 v[214:217], v152 offset:53248
	ds_read_b128 v[218:221], v152 offset:54272
	ds_read_b128 v[222:225], v152 offset:55296
	ds_read_b128 v[226:229], v152 offset:56320
	global_load_lds_dwordx4 v[130:131], off
	s_add_i32 m0, s13, 0x2000
	s_add_u32 s28, s36, 0x40080
	v_lshl_add_u64 v[130:131], v[136:137], 0, s[84:85]
	s_addc_u32 s29, s37, 0
	s_add_i32 s13, s27, s51
	global_load_lds_dwordx4 v[130:131], off
	v_lshl_add_u64 v[130:131], s[28:29], 0, v[142:143]
	s_mov_b32 m0, s13
	s_nop 0
	global_load_lds_dwordx4 v[130:131], off
	v_lshl_add_u64 v[130:131], s[28:29], 0, v[138:139]
	s_add_i32 m0, s13, 0x2000
	s_nop 0
	global_load_lds_dwordx4 v[130:131], off
	v_lshl_add_u64 v[130:131], v[230:231], 0, s[84:85]
	s_mov_b32 m0, s60
	s_nop 0
	global_load_lds_dwordx4 v[130:131], off
	v_lshl_add_u64 v[130:131], v[232:233], 0, s[84:85]
	s_mov_b32 m0, s61
	s_nop 0
	global_load_lds_dwordx4 v[130:131], off
	s_waitcnt vmcnt(8)
	s_waitcnt lgkmcnt(0)
	s_barrier
	s_waitcnt lgkmcnt(0)
	v_mfma_f32_16x16x32_bf16 v[62:65], v[166:169], v[198:201], v[62:65]
	v_mfma_f32_16x16x32_bf16 v[50:53], v[174:177], v[198:201], v[50:53]
	v_mfma_f32_16x16x32_bf16 v[46:49], v[166:169], v[206:209], v[46:49]
	v_mfma_f32_16x16x32_bf16 v[34:37], v[174:177], v[206:209], v[34:37]
	v_mfma_f32_16x16x32_bf16 v[30:33], v[166:169], v[214:217], v[30:33]
	v_mfma_f32_16x16x32_bf16 v[18:21], v[174:177], v[214:217], v[18:21]
	v_mfma_f32_16x16x32_bf16 v[14:17], v[166:169], v[222:225], v[14:17]
	v_mfma_f32_16x16x32_bf16 v[6:9], v[174:177], v[222:225], v[6:9]
	v_mfma_f32_16x16x32_bf16 v[62:65], v[170:173], v[202:205], v[62:65]
	v_mfma_f32_16x16x32_bf16 v[50:53], v[178:181], v[202:205], v[50:53]
	v_mfma_f32_16x16x32_bf16 v[46:49], v[170:173], v[210:213], v[46:49]
	v_mfma_f32_16x16x32_bf16 v[34:37], v[178:181], v[210:213], v[34:37]
	v_mfma_f32_16x16x32_bf16 v[30:33], v[170:173], v[218:221], v[30:33]
	v_mfma_f32_16x16x32_bf16 v[18:21], v[178:181], v[218:221], v[18:21]
	v_mfma_f32_16x16x32_bf16 v[14:17], v[170:173], v[226:229], v[14:17]
	v_mfma_f32_16x16x32_bf16 v[6:9], v[178:181], v[226:229], v[6:9]
	v_mfma_f32_16x16x32_bf16 v[58:61], v[182:185], v[198:201], v[58:61]
	v_mfma_f32_16x16x32_bf16 v[54:57], v[190:193], v[198:201], v[54:57]
	v_mfma_f32_16x16x32_bf16 v[42:45], v[182:185], v[206:209], v[42:45]
	v_mfma_f32_16x16x32_bf16 v[38:41], v[190:193], v[206:209], v[38:41]
	v_mfma_f32_16x16x32_bf16 v[26:29], v[182:185], v[214:217], v[26:29]
	v_mfma_f32_16x16x32_bf16 v[22:25], v[190:193], v[214:217], v[22:25]
	v_mfma_f32_16x16x32_bf16 v[10:13], v[182:185], v[222:225], v[10:13]
	v_mfma_f32_16x16x32_bf16 v[2:5], v[190:193], v[222:225], v[2:5]
	v_mfma_f32_16x16x32_bf16 v[58:61], v[186:189], v[202:205], v[58:61]
	v_mfma_f32_16x16x32_bf16 v[54:57], v[194:197], v[202:205], v[54:57]
	v_mfma_f32_16x16x32_bf16 v[42:45], v[186:189], v[210:213], v[42:45]
	v_mfma_f32_16x16x32_bf16 v[38:41], v[194:197], v[210:213], v[38:41]
	v_mfma_f32_16x16x32_bf16 v[26:29], v[186:189], v[218:221], v[26:29]
	v_mfma_f32_16x16x32_bf16 v[22:25], v[194:197], v[218:221], v[22:25]
	v_mfma_f32_16x16x32_bf16 v[10:13], v[186:189], v[226:229], v[10:13]
	v_mfma_f32_16x16x32_bf16 v[2:5], v[194:197], v[226:229], v[2:5]
	s_barrier
	s_add_i32 s26, s26, 2
	s_add_u32 s10, s10, 0x100
	s_addc_u32 s11, s11, 0
	s_add_u32 s24, s24, 0x100
	s_addc_u32 s25, s25, 0
	s_cmp_gt_u32 s26, 13
	s_cbranch_scc1 .Lffnin_kdone
	.p2alignl 6, 3212836864

.LBB0_148:
	s_ashr_i32 s9, s8, 31
	s_lshl_b64 s[10:11], s[8:9], 19
	s_add_u32 s10, s42, s10
	s_addc_u32 s11, s43, s11
	s_and_b64 s[28:29], s[38:39], exec
	s_cselect_b32 s9, s11, s41
	s_cselect_b32 s27, s10, s40
	s_ashr_i32 s7, s6, 31
	s_lshl_b64 s[28:29], s[6:7], 19
	s_add_u32 s36, s2, s28
	s_addc_u32 s37, s86, s29
	s_and_b64 s[28:29], s[38:39], exec
	s_cselect_b32 s7, s37, s49
	s_cselect_b32 s28, s36, s48
	s_add_u32 s40, s40, 0x40080
	s_addc_u32 s41, s41, 0
	s_add_u32 s29, s48, 0x100
	v_mov_b32_e32 v2, 0
	s_addc_u32 s30, s49, 0
	s_mov_b32 s31, -2
	v_mov_b32_e32 v3, v2
	v_mov_b32_e32 v4, v2
	v_mov_b32_e32 v5, v2
	v_mov_b32_e32 v6, v2
	v_mov_b32_e32 v7, v2
	v_mov_b32_e32 v8, v2
	v_mov_b32_e32 v9, v2
	v_mov_b32_e32 v10, v2
	v_mov_b32_e32 v11, v2
	v_mov_b32_e32 v12, v2
	v_mov_b32_e32 v13, v2
	v_mov_b32_e32 v18, v2
	v_mov_b32_e32 v19, v2
	v_mov_b32_e32 v20, v2
	v_mov_b32_e32 v21, v2
	v_mov_b32_e32 v26, v2
	v_mov_b32_e32 v27, v2
	v_mov_b32_e32 v28, v2
	v_mov_b32_e32 v29, v2
	v_mov_b32_e32 v34, v2
	v_mov_b32_e32 v35, v2
	v_mov_b32_e32 v36, v2
	v_mov_b32_e32 v37, v2
	v_mov_b32_e32 v46, v2
	v_mov_b32_e32 v47, v2
	v_mov_b32_e32 v48, v2
	v_mov_b32_e32 v49, v2
	v_mov_b32_e32 v54, v2
	v_mov_b32_e32 v55, v2
	v_mov_b32_e32 v56, v2
	v_mov_b32_e32 v57, v2
	v_mov_b32_e32 v14, v2
	v_mov_b32_e32 v15, v2
	v_mov_b32_e32 v16, v2
	v_mov_b32_e32 v17, v2
	v_mov_b32_e32 v22, v2
	v_mov_b32_e32 v23, v2
	v_mov_b32_e32 v24, v2
	v_mov_b32_e32 v25, v2
	v_mov_b32_e32 v30, v2
	v_mov_b32_e32 v31, v2
	v_mov_b32_e32 v32, v2
	v_mov_b32_e32 v33, v2
	v_mov_b32_e32 v38, v2
	v_mov_b32_e32 v39, v2
	v_mov_b32_e32 v40, v2
	v_mov_b32_e32 v41, v2
	v_mov_b32_e32 v42, v2
	v_mov_b32_e32 v43, v2
	v_mov_b32_e32 v44, v2
	v_mov_b32_e32 v45, v2
	v_mov_b32_e32 v50, v2
	v_mov_b32_e32 v51, v2
	v_mov_b32_e32 v52, v2
	v_mov_b32_e32 v53, v2
	v_mov_b32_e32 v58, v2
	v_mov_b32_e32 v59, v2
	v_mov_b32_e32 v60, v2
	v_mov_b32_e32 v61, v2
	v_mov_b32_e32 v62, v2
	v_mov_b32_e32 v63, v2
	v_mov_b32_e32 v64, v2
	v_mov_b32_e32 v65, v2
	v_mov_b32_e32 v66, v2
	v_mov_b32_e32 v67, v2
	v_mov_b32_e32 v68, v2
	v_mov_b32_e32 v69, v2
	v_mov_b32_e32 v70, v2
	v_mov_b32_e32 v71, v2
	v_mov_b32_e32 v72, v2
	v_mov_b32_e32 v73, v2
	v_mov_b32_e32 v74, v2
	v_mov_b32_e32 v75, v2
	v_mov_b32_e32 v76, v2
	v_mov_b32_e32 v77, v2
	v_mov_b32_e32 v82, v2
	v_mov_b32_e32 v83, v2
	v_mov_b32_e32 v84, v2
	v_mov_b32_e32 v85, v2
	v_mov_b32_e32 v90, v2
	v_mov_b32_e32 v91, v2
	v_mov_b32_e32 v92, v2
	v_mov_b32_e32 v93, v2
	v_mov_b32_e32 v98, v2
	v_mov_b32_e32 v99, v2
	v_mov_b32_e32 v100, v2
	v_mov_b32_e32 v101, v2
	v_mov_b32_e32 v110, v2
	v_mov_b32_e32 v111, v2
	v_mov_b32_e32 v112, v2
	v_mov_b32_e32 v113, v2
	v_mov_b32_e32 v118, v2
	v_mov_b32_e32 v119, v2
	v_mov_b32_e32 v120, v2
	v_mov_b32_e32 v121, v2
	v_mov_b32_e32 v78, v2
	v_mov_b32_e32 v79, v2
	v_mov_b32_e32 v80, v2
	v_mov_b32_e32 v81, v2
	v_mov_b32_e32 v86, v2
	v_mov_b32_e32 v87, v2
	v_mov_b32_e32 v88, v2
	v_mov_b32_e32 v89, v2
	v_mov_b32_e32 v94, v2
	v_mov_b32_e32 v95, v2
	v_mov_b32_e32 v96, v2
	v_mov_b32_e32 v97, v2
	v_mov_b32_e32 v102, v2
	v_mov_b32_e32 v103, v2
	v_mov_b32_e32 v104, v2
	v_mov_b32_e32 v105, v2
	v_mov_b32_e32 v106, v2
	v_mov_b32_e32 v107, v2
	v_mov_b32_e32 v108, v2
	v_mov_b32_e32 v109, v2
	v_mov_b32_e32 v114, v2
	v_mov_b32_e32 v115, v2
	v_mov_b32_e32 v116, v2
	v_mov_b32_e32 v117, v2
	v_mov_b32_e32 v122, v2
	v_mov_b32_e32 v123, v2
	v_mov_b32_e32 v124, v2
	v_mov_b32_e32 v125, v2
	v_mov_b32_e32 v126, v2
	v_mov_b32_e32 v127, v2
	v_mov_b32_e32 v128, v2
	v_mov_b32_e32 v129, v2
	.p2alignl 6, 3212836864

.LBB0_172:
	s_ashr_i32 s5, s4, 31
	s_lshl_b64 s[6:7], s[4:5], 19
	v_readlane_b32 s1, v253, 60
	s_add_u32 s6, s1, s6
	v_readlane_b32 s1, v253, 61
	s_addc_u32 s7, s1, s7
	s_and_b64 s[8:9], s[38:39], exec
	s_cselect_b32 s5, s7, s11
	s_cselect_b32 s21, s6, s10
	s_ashr_i32 s1, s0, 31
	s_lshl_b64 s[8:9], s[0:1], 19
	s_add_u32 s8, s42, s8
	s_addc_u32 s9, s43, s9
	s_and_b64 s[22:23], s[38:39], exec
	s_cselect_b32 s1, s9, s41
	s_cselect_b32 s22, s8, s40
	s_add_u32 s10, s10, 0x40080
	s_addc_u32 s11, s11, 0
	s_add_u32 s23, s40, 0x100
	v_mov_b32_e32 v2, 0
	s_addc_u32 s24, s41, 0
	s_mov_b32 s25, -2
	v_mov_b32_e32 v3, v2
	v_mov_b32_e32 v4, v2
	v_mov_b32_e32 v5, v2
	v_mov_b32_e32 v6, v2
	v_mov_b32_e32 v7, v2
	v_mov_b32_e32 v8, v2
	v_mov_b32_e32 v9, v2
	v_mov_b32_e32 v10, v2
	v_mov_b32_e32 v11, v2
	v_mov_b32_e32 v12, v2
	v_mov_b32_e32 v13, v2
	v_mov_b32_e32 v14, v2
	v_mov_b32_e32 v15, v2
	v_mov_b32_e32 v16, v2
	v_mov_b32_e32 v17, v2
	v_mov_b32_e32 v18, v2
	v_mov_b32_e32 v19, v2
	v_mov_b32_e32 v20, v2
	v_mov_b32_e32 v21, v2
	v_mov_b32_e32 v22, v2
	v_mov_b32_e32 v23, v2
	v_mov_b32_e32 v24, v2
	v_mov_b32_e32 v25, v2
	v_mov_b32_e32 v26, v2
	v_mov_b32_e32 v27, v2
	v_mov_b32_e32 v28, v2
	v_mov_b32_e32 v29, v2
	v_mov_b32_e32 v30, v2
	v_mov_b32_e32 v31, v2
	v_mov_b32_e32 v32, v2
	v_mov_b32_e32 v33, v2
	v_mov_b32_e32 v66, v2
	v_mov_b32_e32 v67, v2
	v_mov_b32_e32 v68, v2
	v_mov_b32_e32 v69, v2
	v_mov_b32_e32 v70, v2
	v_mov_b32_e32 v71, v2
	v_mov_b32_e32 v72, v2
	v_mov_b32_e32 v73, v2
	v_mov_b32_e32 v74, v2
	v_mov_b32_e32 v75, v2
	v_mov_b32_e32 v76, v2
	v_mov_b32_e32 v77, v2
	v_mov_b32_e32 v78, v2
	v_mov_b32_e32 v79, v2
	v_mov_b32_e32 v80, v2
	v_mov_b32_e32 v81, v2
	v_mov_b32_e32 v82, v2
	v_mov_b32_e32 v83, v2
	v_mov_b32_e32 v84, v2
	v_mov_b32_e32 v85, v2
	v_mov_b32_e32 v86, v2
	v_mov_b32_e32 v87, v2
	v_mov_b32_e32 v88, v2
	v_mov_b32_e32 v89, v2
	v_mov_b32_e32 v90, v2
	v_mov_b32_e32 v91, v2
	v_mov_b32_e32 v92, v2
	v_mov_b32_e32 v93, v2
	v_mov_b32_e32 v94, v2
	v_mov_b32_e32 v95, v2
	v_mov_b32_e32 v96, v2
	v_mov_b32_e32 v97, v2
	v_mov_b32_e32 v34, v2
	v_mov_b32_e32 v35, v2
	v_mov_b32_e32 v36, v2
	v_mov_b32_e32 v37, v2
	v_mov_b32_e32 v38, v2
	v_mov_b32_e32 v39, v2
	v_mov_b32_e32 v40, v2
	v_mov_b32_e32 v41, v2
	v_mov_b32_e32 v42, v2
	v_mov_b32_e32 v43, v2
	v_mov_b32_e32 v44, v2
	v_mov_b32_e32 v45, v2
	v_mov_b32_e32 v46, v2
	v_mov_b32_e32 v47, v2
	v_mov_b32_e32 v48, v2
	v_mov_b32_e32 v49, v2
	v_mov_b32_e32 v50, v2
	v_mov_b32_e32 v51, v2
	v_mov_b32_e32 v52, v2
	v_mov_b32_e32 v53, v2
	v_mov_b32_e32 v54, v2
	v_mov_b32_e32 v55, v2
	v_mov_b32_e32 v56, v2
	v_mov_b32_e32 v57, v2
	v_mov_b32_e32 v58, v2
	v_mov_b32_e32 v59, v2
	v_mov_b32_e32 v60, v2
	v_mov_b32_e32 v61, v2
	v_mov_b32_e32 v62, v2
	v_mov_b32_e32 v63, v2
	v_mov_b32_e32 v64, v2
	v_mov_b32_e32 v65, v2
	v_mov_b32_e32 v98, v2
	v_mov_b32_e32 v99, v2
	v_mov_b32_e32 v100, v2
	v_mov_b32_e32 v101, v2
	v_mov_b32_e32 v102, v2
	v_mov_b32_e32 v103, v2
	v_mov_b32_e32 v104, v2
	v_mov_b32_e32 v105, v2
	v_mov_b32_e32 v106, v2
	v_mov_b32_e32 v107, v2
	v_mov_b32_e32 v108, v2
	v_mov_b32_e32 v109, v2
	v_mov_b32_e32 v110, v2
	v_mov_b32_e32 v111, v2
	v_mov_b32_e32 v112, v2
	v_mov_b32_e32 v113, v2
	v_mov_b32_e32 v114, v2
	v_mov_b32_e32 v115, v2
	v_mov_b32_e32 v116, v2
	v_mov_b32_e32 v117, v2
	v_mov_b32_e32 v118, v2
	v_mov_b32_e32 v119, v2
	v_mov_b32_e32 v120, v2
	v_mov_b32_e32 v121, v2
	v_mov_b32_e32 v122, v2
	v_mov_b32_e32 v123, v2
	v_mov_b32_e32 v124, v2
	v_mov_b32_e32 v125, v2
	v_mov_b32_e32 v126, v2
	v_mov_b32_e32 v127, v2
	v_mov_b32_e32 v128, v2
	v_mov_b32_e32 v129, v2
	.p2alignl 6, 3212836864

.LBB0_270:
	s_ashr_i32 s9, s8, 31
	s_lshl_b64 s[10:11], s[8:9], 21
	s_add_u32 s10, s33, s10
	s_addc_u32 s11, s96, s11
	s_and_b64 s[28:29], s[40:41], exec
	s_cselect_b32 s9, s11, s51
	s_cselect_b32 s27, s10, s50
	s_ashr_i32 s7, s6, 31
	s_lshl_b64 s[28:29], s[6:7], 21
	s_add_u32 s36, s52, s28
	s_addc_u32 s37, s53, s29
	s_and_b64 s[28:29], s[40:41], exec
	s_cselect_b32 s7, s37, s49
	s_cselect_b32 s28, s36, s48
	s_add_u32 s29, s48, 0x100
	s_addc_u32 s30, s49, 0
	s_add_u32 s82, s50, 0x100800
	v_mov_b32_e32 v2, 0
	s_addc_u32 s83, s51, 0
	s_mov_b32 s31, -2
	v_mov_b32_e32 v3, v2
	v_mov_b32_e32 v4, v2
	v_mov_b32_e32 v5, v2
	v_mov_b32_e32 v6, v2
	v_mov_b32_e32 v7, v2
	v_mov_b32_e32 v8, v2
	v_mov_b32_e32 v9, v2
	v_mov_b32_e32 v18, v2
	v_mov_b32_e32 v19, v2
	v_mov_b32_e32 v20, v2
	v_mov_b32_e32 v21, v2
	v_mov_b32_e32 v22, v2
	v_mov_b32_e32 v23, v2
	v_mov_b32_e32 v24, v2
	v_mov_b32_e32 v25, v2
	v_mov_b32_e32 v34, v2
	v_mov_b32_e32 v35, v2
	v_mov_b32_e32 v36, v2
	v_mov_b32_e32 v37, v2
	v_mov_b32_e32 v38, v2
	v_mov_b32_e32 v39, v2
	v_mov_b32_e32 v40, v2
	v_mov_b32_e32 v41, v2
	v_mov_b32_e32 v50, v2
	v_mov_b32_e32 v51, v2
	v_mov_b32_e32 v52, v2
	v_mov_b32_e32 v53, v2
	v_mov_b32_e32 v54, v2
	v_mov_b32_e32 v55, v2
	v_mov_b32_e32 v56, v2
	v_mov_b32_e32 v57, v2
	v_mov_b32_e32 v10, v2
	v_mov_b32_e32 v11, v2
	v_mov_b32_e32 v12, v2
	v_mov_b32_e32 v13, v2
	v_mov_b32_e32 v14, v2
	v_mov_b32_e32 v15, v2
	v_mov_b32_e32 v16, v2
	v_mov_b32_e32 v17, v2
	v_mov_b32_e32 v26, v2
	v_mov_b32_e32 v27, v2
	v_mov_b32_e32 v28, v2
	v_mov_b32_e32 v29, v2
	v_mov_b32_e32 v30, v2
	v_mov_b32_e32 v31, v2
	v_mov_b32_e32 v32, v2
	v_mov_b32_e32 v33, v2
	v_mov_b32_e32 v42, v2
	v_mov_b32_e32 v43, v2
	v_mov_b32_e32 v44, v2
	v_mov_b32_e32 v45, v2
	v_mov_b32_e32 v46, v2
	v_mov_b32_e32 v47, v2
	v_mov_b32_e32 v48, v2
	v_mov_b32_e32 v49, v2
	v_mov_b32_e32 v58, v2
	v_mov_b32_e32 v59, v2
	v_mov_b32_e32 v60, v2
	v_mov_b32_e32 v61, v2
	v_mov_b32_e32 v62, v2
	v_mov_b32_e32 v63, v2
	v_mov_b32_e32 v64, v2
	v_mov_b32_e32 v65, v2
	v_mov_b32_e32 v66, v2
	v_mov_b32_e32 v67, v2
	v_mov_b32_e32 v68, v2
	v_mov_b32_e32 v69, v2
	v_mov_b32_e32 v70, v2
	v_mov_b32_e32 v71, v2
	v_mov_b32_e32 v72, v2
	v_mov_b32_e32 v73, v2
	v_mov_b32_e32 v82, v2
	v_mov_b32_e32 v83, v2
	v_mov_b32_e32 v84, v2
	v_mov_b32_e32 v85, v2
	v_mov_b32_e32 v86, v2
	v_mov_b32_e32 v87, v2
	v_mov_b32_e32 v88, v2
	v_mov_b32_e32 v89, v2
	v_mov_b32_e32 v102, v2
	v_mov_b32_e32 v103, v2
	v_mov_b32_e32 v104, v2
	v_mov_b32_e32 v105, v2
	v_mov_b32_e32 v110, v2
	v_mov_b32_e32 v111, v2
	v_mov_b32_e32 v112, v2
	v_mov_b32_e32 v113, v2
	v_mov_b32_e32 v130, v2
	v_mov_b32_e32 v131, v2
	v_mov_b32_e32 v132, v2
	v_mov_b32_e32 v133, v2
	v_mov_b32_e32 v134, v2
	v_mov_b32_e32 v135, v2
	v_mov_b32_e32 v136, v2
	v_mov_b32_e32 v137, v2
	v_mov_b32_e32 v74, v2
	v_mov_b32_e32 v75, v2
	v_mov_b32_e32 v76, v2
	v_mov_b32_e32 v77, v2
	v_mov_b32_e32 v78, v2
	v_mov_b32_e32 v79, v2
	v_mov_b32_e32 v80, v2
	v_mov_b32_e32 v81, v2
	v_mov_b32_e32 v90, v2
	v_mov_b32_e32 v91, v2
	v_mov_b32_e32 v92, v2
	v_mov_b32_e32 v93, v2
	v_mov_b32_e32 v98, v2
	v_mov_b32_e32 v99, v2
	v_mov_b32_e32 v100, v2
	v_mov_b32_e32 v101, v2
	v_mov_b32_e32 v118, v2
	v_mov_b32_e32 v119, v2
	v_mov_b32_e32 v120, v2
	v_mov_b32_e32 v121, v2
	v_mov_b32_e32 v122, v2
	v_mov_b32_e32 v123, v2
	v_mov_b32_e32 v124, v2
	v_mov_b32_e32 v125, v2
	v_mov_b32_e32 v146, v2
	v_mov_b32_e32 v147, v2
	v_mov_b32_e32 v148, v2
	v_mov_b32_e32 v149, v2
	v_mov_b32_e32 v154, v2
	v_mov_b32_e32 v155, v2
	v_mov_b32_e32 v156, v2
	v_mov_b32_e32 v157, v2
	.p2alignl 6, 3212836864

.LBB0_307:
	s_ashr_i32 s9, s8, 31
	s_lshl_b64 s[10:11], s[8:9], 17
	s_add_u32 s10, s71, s10
	s_addc_u32 s11, s79, s11
	s_and_b64 s[34:35], s[40:41], exec
	s_cselect_b32 s9, s11, s45
	s_cselect_b32 s31, s10, s44
	s_ashr_i32 s7, s6, 31
	s_lshl_b64 s[34:35], s[6:7], 17
	v_readlane_b32 s3, v254, 33
	s_add_u32 s36, s3, s34
	v_readlane_b32 s3, v254, 34
	s_addc_u32 s37, s3, s35
	s_and_b64 s[34:35], s[40:41], exec
	v_mov_b32_e32 v2, 0
	s_mov_b64 s[14:15], s[92:93]
	s_mov_b32 s12, s97
	s_cselect_b32 s7, s37, s43
	s_cselect_b32 s34, s36, s42
	s_mov_b32 s35, 0
	s_mov_b64 s[82:83], -1
	s_mov_b64 s[48:49], 0
	v_mov_b32_e32 v3, v2
	v_mov_b32_e32 v4, v2
	v_mov_b32_e32 v5, v2
	v_mov_b32_e32 v6, v2
	v_mov_b32_e32 v7, v2
	v_mov_b32_e32 v8, v2
	v_mov_b32_e32 v9, v2
	v_mov_b32_e32 v10, v2
	v_mov_b32_e32 v11, v2
	v_mov_b32_e32 v12, v2
	v_mov_b32_e32 v13, v2
	v_mov_b32_e32 v14, v2
	v_mov_b32_e32 v15, v2
	v_mov_b32_e32 v16, v2
	v_mov_b32_e32 v17, v2
	v_mov_b32_e32 v26, v2
	v_mov_b32_e32 v27, v2
	v_mov_b32_e32 v28, v2
	v_mov_b32_e32 v29, v2
	v_mov_b32_e32 v30, v2
	v_mov_b32_e32 v31, v2
	v_mov_b32_e32 v32, v2
	v_mov_b32_e32 v33, v2
	v_mov_b32_e32 v42, v2
	v_mov_b32_e32 v43, v2
	v_mov_b32_e32 v44, v2
	v_mov_b32_e32 v45, v2
	v_mov_b32_e32 v46, v2
	v_mov_b32_e32 v47, v2
	v_mov_b32_e32 v48, v2
	v_mov_b32_e32 v49, v2
	v_mov_b32_e32 v18, v2
	v_mov_b32_e32 v19, v2
	v_mov_b32_e32 v20, v2
	v_mov_b32_e32 v21, v2
	v_mov_b32_e32 v22, v2
	v_mov_b32_e32 v23, v2
	v_mov_b32_e32 v24, v2
	v_mov_b32_e32 v25, v2
	v_mov_b32_e32 v34, v2
	v_mov_b32_e32 v35, v2
	v_mov_b32_e32 v36, v2
	v_mov_b32_e32 v37, v2
	v_mov_b32_e32 v38, v2
	v_mov_b32_e32 v39, v2
	v_mov_b32_e32 v40, v2
	v_mov_b32_e32 v41, v2
	v_mov_b32_e32 v50, v2
	v_mov_b32_e32 v51, v2
	v_mov_b32_e32 v52, v2
	v_mov_b32_e32 v53, v2
	v_mov_b32_e32 v54, v2
	v_mov_b32_e32 v55, v2
	v_mov_b32_e32 v56, v2
	v_mov_b32_e32 v57, v2
	v_mov_b32_e32 v58, v2
	v_mov_b32_e32 v59, v2
	v_mov_b32_e32 v60, v2
	v_mov_b32_e32 v61, v2
	v_mov_b32_e32 v62, v2
	v_mov_b32_e32 v63, v2
	v_mov_b32_e32 v64, v2
	v_mov_b32_e32 v65, v2
	v_mov_b32_e32 v66, v2
	v_mov_b32_e32 v67, v2
	v_mov_b32_e32 v68, v2
	v_mov_b32_e32 v69, v2
	v_mov_b32_e32 v70, v2
	v_mov_b32_e32 v71, v2
	v_mov_b32_e32 v72, v2
	v_mov_b32_e32 v73, v2
	v_mov_b32_e32 v74, v2
	v_mov_b32_e32 v75, v2
	v_mov_b32_e32 v76, v2
	v_mov_b32_e32 v77, v2
	v_mov_b32_e32 v78, v2
	v_mov_b32_e32 v79, v2
	v_mov_b32_e32 v80, v2
	v_mov_b32_e32 v81, v2
	v_mov_b32_e32 v90, v2
	v_mov_b32_e32 v91, v2
	v_mov_b32_e32 v92, v2
	v_mov_b32_e32 v93, v2
	v_mov_b32_e32 v94, v2
	v_mov_b32_e32 v95, v2
	v_mov_b32_e32 v96, v2
	v_mov_b32_e32 v97, v2
	v_mov_b32_e32 v106, v2
	v_mov_b32_e32 v107, v2
	v_mov_b32_e32 v108, v2
	v_mov_b32_e32 v109, v2
	v_mov_b32_e32 v110, v2
	v_mov_b32_e32 v111, v2
	v_mov_b32_e32 v112, v2
	v_mov_b32_e32 v113, v2
	v_mov_b32_e32 v82, v2
	v_mov_b32_e32 v83, v2
	v_mov_b32_e32 v84, v2
	v_mov_b32_e32 v85, v2
	v_mov_b32_e32 v86, v2
	v_mov_b32_e32 v87, v2
	v_mov_b32_e32 v88, v2
	v_mov_b32_e32 v89, v2
	v_mov_b32_e32 v98, v2
	v_mov_b32_e32 v99, v2
	v_mov_b32_e32 v100, v2
	v_mov_b32_e32 v101, v2
	v_mov_b32_e32 v102, v2
	v_mov_b32_e32 v103, v2
	v_mov_b32_e32 v104, v2
	v_mov_b32_e32 v105, v2
	v_mov_b32_e32 v114, v2
	v_mov_b32_e32 v115, v2
	v_mov_b32_e32 v116, v2
	v_mov_b32_e32 v117, v2
	v_mov_b32_e32 v118, v2
	v_mov_b32_e32 v119, v2
	v_mov_b32_e32 v120, v2
	v_mov_b32_e32 v121, v2
	v_mov_b32_e32 v122, v2
	v_mov_b32_e32 v123, v2
	v_mov_b32_e32 v124, v2
	v_mov_b32_e32 v125, v2
	v_mov_b32_e32 v126, v2
	v_mov_b32_e32 v127, v2
	v_mov_b32_e32 v128, v2
	v_mov_b32_e32 v129, v2
	.p2alignl 6, 3212836864

.LBB0_407:
	s_ashr_i32 s11, s10, 31
	s_lshl_b64 s[28:29], s[10:11], 19
	s_add_u32 s36, s88, s28
	s_addc_u32 s37, s89, s29
	s_and_b64 s[28:29], s[40:41], exec
	s_cselect_b32 s11, s37, s45
	s_cselect_b32 s27, s36, s44
	s_ashr_i32 s9, s8, 31
	s_lshl_b64 s[28:29], s[8:9], 19
	s_add_u32 s42, s1, s28
	s_addc_u32 s43, s19, s29
	s_and_b64 s[28:29], s[40:41], exec
	s_cselect_b32 s9, s43, s49
	s_cselect_b32 s28, s42, s48
	s_add_u32 s44, s44, 0x40080
	s_addc_u32 s45, s45, 0
	s_add_u32 s29, s48, 0x100
	v_mov_b32_e32 v2, 0
	s_addc_u32 s30, s49, 0
	s_mov_b32 s31, -2
	v_mov_b32_e32 v3, v2
	v_mov_b32_e32 v4, v2
	v_mov_b32_e32 v5, v2
	v_mov_b32_e32 v6, v2
	v_mov_b32_e32 v7, v2
	v_mov_b32_e32 v8, v2
	v_mov_b32_e32 v9, v2
	v_mov_b32_e32 v10, v2
	v_mov_b32_e32 v11, v2
	v_mov_b32_e32 v12, v2
	v_mov_b32_e32 v13, v2
	v_mov_b32_e32 v18, v2
	v_mov_b32_e32 v19, v2
	v_mov_b32_e32 v20, v2
	v_mov_b32_e32 v21, v2
	v_mov_b32_e32 v26, v2
	v_mov_b32_e32 v27, v2
	v_mov_b32_e32 v28, v2
	v_mov_b32_e32 v29, v2
	v_mov_b32_e32 v34, v2
	v_mov_b32_e32 v35, v2
	v_mov_b32_e32 v36, v2
	v_mov_b32_e32 v37, v2
	v_mov_b32_e32 v46, v2
	v_mov_b32_e32 v47, v2
	v_mov_b32_e32 v48, v2
	v_mov_b32_e32 v49, v2
	v_mov_b32_e32 v54, v2
	v_mov_b32_e32 v55, v2
	v_mov_b32_e32 v56, v2
	v_mov_b32_e32 v57, v2
	v_mov_b32_e32 v14, v2
	v_mov_b32_e32 v15, v2
	v_mov_b32_e32 v16, v2
	v_mov_b32_e32 v17, v2
	v_mov_b32_e32 v22, v2
	v_mov_b32_e32 v23, v2
	v_mov_b32_e32 v24, v2
	v_mov_b32_e32 v25, v2
	v_mov_b32_e32 v30, v2
	v_mov_b32_e32 v31, v2
	v_mov_b32_e32 v32, v2
	v_mov_b32_e32 v33, v2
	v_mov_b32_e32 v38, v2
	v_mov_b32_e32 v39, v2
	v_mov_b32_e32 v40, v2
	v_mov_b32_e32 v41, v2
	v_mov_b32_e32 v42, v2
	v_mov_b32_e32 v43, v2
	v_mov_b32_e32 v44, v2
	v_mov_b32_e32 v45, v2
	v_mov_b32_e32 v50, v2
	v_mov_b32_e32 v51, v2
	v_mov_b32_e32 v52, v2
	v_mov_b32_e32 v53, v2
	v_mov_b32_e32 v58, v2
	v_mov_b32_e32 v59, v2
	v_mov_b32_e32 v60, v2
	v_mov_b32_e32 v61, v2
	v_mov_b32_e32 v62, v2
	v_mov_b32_e32 v63, v2
	v_mov_b32_e32 v64, v2
	v_mov_b32_e32 v65, v2
	v_mov_b32_e32 v66, v2
	v_mov_b32_e32 v67, v2
	v_mov_b32_e32 v68, v2
	v_mov_b32_e32 v69, v2
	v_mov_b32_e32 v70, v2
	v_mov_b32_e32 v71, v2
	v_mov_b32_e32 v72, v2
	v_mov_b32_e32 v73, v2
	v_mov_b32_e32 v74, v2
	v_mov_b32_e32 v75, v2
	v_mov_b32_e32 v76, v2
	v_mov_b32_e32 v77, v2
	v_mov_b32_e32 v82, v2
	v_mov_b32_e32 v83, v2
	v_mov_b32_e32 v84, v2
	v_mov_b32_e32 v85, v2
	v_mov_b32_e32 v90, v2
	v_mov_b32_e32 v91, v2
	v_mov_b32_e32 v92, v2
	v_mov_b32_e32 v93, v2
	v_mov_b32_e32 v98, v2
	v_mov_b32_e32 v99, v2
	v_mov_b32_e32 v100, v2
	v_mov_b32_e32 v101, v2
	v_mov_b32_e32 v110, v2
	v_mov_b32_e32 v111, v2
	v_mov_b32_e32 v112, v2
	v_mov_b32_e32 v113, v2
	v_mov_b32_e32 v118, v2
	v_mov_b32_e32 v119, v2
	v_mov_b32_e32 v120, v2
	v_mov_b32_e32 v121, v2
	v_mov_b32_e32 v78, v2
	v_mov_b32_e32 v79, v2
	v_mov_b32_e32 v80, v2
	v_mov_b32_e32 v81, v2
	v_mov_b32_e32 v86, v2
	v_mov_b32_e32 v87, v2
	v_mov_b32_e32 v88, v2
	v_mov_b32_e32 v89, v2
	v_mov_b32_e32 v94, v2
	v_mov_b32_e32 v95, v2
	v_mov_b32_e32 v96, v2
	v_mov_b32_e32 v97, v2
	v_mov_b32_e32 v102, v2
	v_mov_b32_e32 v103, v2
	v_mov_b32_e32 v104, v2
	v_mov_b32_e32 v105, v2
	v_mov_b32_e32 v106, v2
	v_mov_b32_e32 v107, v2
	v_mov_b32_e32 v108, v2
	v_mov_b32_e32 v109, v2
	v_mov_b32_e32 v114, v2
	v_mov_b32_e32 v115, v2
	v_mov_b32_e32 v116, v2
	v_mov_b32_e32 v117, v2
	v_mov_b32_e32 v122, v2
	v_mov_b32_e32 v123, v2
	v_mov_b32_e32 v124, v2
	v_mov_b32_e32 v125, v2
	v_mov_b32_e32 v126, v2
	v_mov_b32_e32 v127, v2
	v_mov_b32_e32 v128, v2
	v_mov_b32_e32 v129, v2
	.p2alignl 6, 3212836864

.LBB0_508:
	s_or_b64 exec, exec, s[48:49]
	v_lshl_add_u64 v[12:13], v[134:135], 0, s[44:45]
	v_lshl_add_u64 v[8:9], v[140:141], 1, v[12:13]
	global_load_dwordx4 v[66:69], v[8:9], off
	v_lshl_add_u64 v[8:9], v[142:143], 1, v[12:13]
	global_load_dwordx4 v[70:73], v[8:9], off
	v_lshl_add_u64 v[8:9], v[144:145], 1, v[12:13]
	global_load_dwordx4 v[74:77], v[8:9], off
	v_lshl_add_u64 v[8:9], v[146:147], 1, v[12:13]
	global_load_dwordx4 v[78:81], v[8:9], off
	s_add_i32 s24, s58, s13
	s_ashr_i32 s25, s24, 31
	s_lshl_b64 s[24:25], s[24:25], 18
	v_mov_b32_e32 v14, v1
	v_mov_b32_e32 v15, v1
	v_lshl_add_u64 v[130:131], v[6:7], 1, s[4:5]
	v_lshl_add_u64 v[132:133], v[4:5], 1, s[4:5]
	v_lshl_add_u64 v[152:153], v[2:3], 1, s[24:25]
	v_mov_b32_e32 v0, v1
	v_mov_b32_e32 v2, v1
	v_mov_b32_e32 v3, v1
	v_mov_b32_e32 v4, v1
	v_mov_b32_e32 v5, v1
	v_mov_b32_e32 v6, v1
	v_mov_b32_e32 v7, v1
	s_xor_b64 s[10:11], s[10:11], -1
	s_mov_b32 s23, 0
	v_mov_b32_e32 v154, 0
	s_mov_b32 s24, 2
	s_mov_b32 s25, s20
	s_mov_b32 s26, 0
	v_mov_b32_e32 v155, 0
	s_mov_b32 s27, 0
	s_waitcnt vmcnt(0)
	ds_write_b128 v215, v[66:69]
	ds_write_b128 v216, v[70:73]
	ds_write_b128 v217, v[74:77]
	ds_write_b128 v218, v[78:81]
	v_mov_b32_e32 v12, v1
	v_mov_b32_e32 v13, v1
	v_mov_b32_e32 v8, v1
	v_mov_b32_e32 v9, v1
	v_mov_b32_e32 v10, v1
	v_mov_b32_e32 v11, v1
	v_mov_b64_e32 v[64:65], v[14:15]
	v_mov_b64_e32 v[48:49], v[14:15]
	v_mov_b64_e32 v[32:33], v[14:15]
	v_mov_b64_e32 v[62:63], v[12:13]
	v_mov_b64_e32 v[60:61], v[10:11]
	v_mov_b64_e32 v[58:59], v[8:9]
	v_mov_b64_e32 v[56:57], v[6:7]
	v_mov_b64_e32 v[54:55], v[4:5]
	v_mov_b64_e32 v[52:53], v[2:3]
	v_mov_b64_e32 v[50:51], v[0:1]
	v_mov_b64_e32 v[46:47], v[12:13]
	v_mov_b64_e32 v[44:45], v[10:11]
	v_mov_b64_e32 v[42:43], v[8:9]
	v_mov_b64_e32 v[40:41], v[6:7]
	v_mov_b64_e32 v[38:39], v[4:5]
	v_mov_b64_e32 v[36:37], v[2:3]
	v_mov_b64_e32 v[34:35], v[0:1]
	v_mov_b64_e32 v[30:31], v[12:13]
	v_mov_b64_e32 v[28:29], v[10:11]
	v_mov_b64_e32 v[26:27], v[8:9]
	v_mov_b64_e32 v[24:25], v[6:7]
	v_mov_b64_e32 v[22:23], v[4:5]
	v_mov_b64_e32 v[20:21], v[2:3]
	v_mov_b64_e32 v[18:19], v[0:1]
	v_mov_b64_e32 v[16:17], v[14:15]
	v_mov_b64_e32 v[14:15], v[12:13]
	v_mov_b64_e32 v[12:13], v[10:11]
	v_mov_b64_e32 v[10:11], v[8:9]
	v_mov_b64_e32 v[8:9], v[6:7]
	v_mov_b64_e32 v[6:7], v[4:5]
	v_mov_b64_e32 v[4:5], v[2:3]
	v_mov_b64_e32 v[2:3], v[0:1]
	s_branch .LBB0_511
	.p2alignl 6, 3212836864

.LBB0_510:
	s_add_i32 s13, s27, 1
	s_cmp_lg_u32 s27, 3
	s_cselect_b32 s27, s13, 0
	s_addk_i32 s26, 0xff00
	s_add_i32 s24, s24, 1
	s_add_i32 s13, s21, s26
	s_sub_i32 s25, s25, 64
	s_add_i32 s23, s23, 64
	v_lshl_add_u64 v[130:131], v[130:131], 0, s[56:57]
	v_lshl_add_u64 v[132:133], v[132:133], 0, s[56:57]
	s_cmpk_eq_i32 s13, 0xfc00
	v_lshl_add_u64 v[152:153], v[152:153], 0, s[90:91]
	s_cbranch_scc1 .LBB0_525
	.p2alignl 6, 3212836864

.LBB0_621:
	s_ashr_i32 s9, s8, 31
	s_lshl_b64 s[10:11], s[8:9], 19
	s_add_u32 s10, s88, s10
	s_addc_u32 s11, s89, s11
	s_and_b64 s[26:27], s[42:43], exec
	s_cselect_b32 s9, s11, s41
	s_cselect_b32 s26, s10, s40
	s_ashr_i32 s7, s6, 31
	s_lshl_b64 s[28:29], s[6:7], 19
	v_readlane_b32 s3, v254, 45
	s_add_u32 s36, s3, s28
	v_readlane_b32 s3, v254, 46
	s_addc_u32 s37, s3, s29
	s_and_b64 s[28:29], s[42:43], exec
	s_cselect_b32 s7, s37, s45
	s_cselect_b32 s27, s36, s44
	s_add_u32 s40, s40, 0x40080
	s_addc_u32 s41, s41, 0
	s_add_u32 s28, s44, 0x100
	v_mov_b32_e32 v2, 0
	s_addc_u32 s29, s45, 0
	s_mov_b32 s30, -2
	v_mov_b32_e32 v3, v2
	v_mov_b32_e32 v4, v2
	v_mov_b32_e32 v5, v2
	v_mov_b32_e32 v10, v2
	v_mov_b32_e32 v11, v2
	v_mov_b32_e32 v12, v2
	v_mov_b32_e32 v13, v2
	v_mov_b32_e32 v18, v2
	v_mov_b32_e32 v19, v2
	v_mov_b32_e32 v20, v2
	v_mov_b32_e32 v21, v2
	v_mov_b32_e32 v26, v2
	v_mov_b32_e32 v27, v2
	v_mov_b32_e32 v28, v2
	v_mov_b32_e32 v29, v2
	v_mov_b32_e32 v34, v2
	v_mov_b32_e32 v35, v2
	v_mov_b32_e32 v36, v2
	v_mov_b32_e32 v37, v2
	v_mov_b32_e32 v42, v2
	v_mov_b32_e32 v43, v2
	v_mov_b32_e32 v44, v2
	v_mov_b32_e32 v45, v2
	v_mov_b32_e32 v50, v2
	v_mov_b32_e32 v51, v2
	v_mov_b32_e32 v52, v2
	v_mov_b32_e32 v53, v2
	v_mov_b32_e32 v58, v2
	v_mov_b32_e32 v59, v2
	v_mov_b32_e32 v60, v2
	v_mov_b32_e32 v61, v2
	v_mov_b32_e32 v6, v2
	v_mov_b32_e32 v7, v2
	v_mov_b32_e32 v8, v2
	v_mov_b32_e32 v9, v2
	v_mov_b32_e32 v14, v2
	v_mov_b32_e32 v15, v2
	v_mov_b32_e32 v16, v2
	v_mov_b32_e32 v17, v2
	v_mov_b32_e32 v22, v2
	v_mov_b32_e32 v23, v2
	v_mov_b32_e32 v24, v2
	v_mov_b32_e32 v25, v2
	v_mov_b32_e32 v30, v2
	v_mov_b32_e32 v31, v2
	v_mov_b32_e32 v32, v2
	v_mov_b32_e32 v33, v2
	v_mov_b32_e32 v38, v2
	v_mov_b32_e32 v39, v2
	v_mov_b32_e32 v40, v2
	v_mov_b32_e32 v41, v2
	v_mov_b32_e32 v46, v2
	v_mov_b32_e32 v47, v2
	v_mov_b32_e32 v48, v2
	v_mov_b32_e32 v49, v2
	v_mov_b32_e32 v54, v2
	v_mov_b32_e32 v55, v2
	v_mov_b32_e32 v56, v2
	v_mov_b32_e32 v57, v2
	v_mov_b32_e32 v62, v2
	v_mov_b32_e32 v63, v2
	v_mov_b32_e32 v64, v2
	v_mov_b32_e32 v65, v2
	v_mov_b32_e32 v66, v2
	v_mov_b32_e32 v67, v2
	v_mov_b32_e32 v68, v2
	v_mov_b32_e32 v69, v2
	v_mov_b32_e32 v74, v2
	v_mov_b32_e32 v75, v2
	v_mov_b32_e32 v76, v2
	v_mov_b32_e32 v77, v2
	v_mov_b32_e32 v82, v2
	v_mov_b32_e32 v83, v2
	v_mov_b32_e32 v84, v2
	v_mov_b32_e32 v85, v2
	v_mov_b32_e32 v90, v2
	v_mov_b32_e32 v91, v2
	v_mov_b32_e32 v92, v2
	v_mov_b32_e32 v93, v2
	v_mov_b32_e32 v98, v2
	v_mov_b32_e32 v99, v2
	v_mov_b32_e32 v100, v2
	v_mov_b32_e32 v101, v2
	v_mov_b32_e32 v106, v2
	v_mov_b32_e32 v107, v2
	v_mov_b32_e32 v108, v2
	v_mov_b32_e32 v109, v2
	v_mov_b32_e32 v114, v2
	v_mov_b32_e32 v115, v2
	v_mov_b32_e32 v116, v2
	v_mov_b32_e32 v117, v2
	v_mov_b32_e32 v122, v2
	v_mov_b32_e32 v123, v2
	v_mov_b32_e32 v124, v2
	v_mov_b32_e32 v125, v2
	v_mov_b32_e32 v70, v2
	v_mov_b32_e32 v71, v2
	v_mov_b32_e32 v72, v2
	v_mov_b32_e32 v73, v2
	v_mov_b32_e32 v78, v2
	v_mov_b32_e32 v79, v2
	v_mov_b32_e32 v80, v2
	v_mov_b32_e32 v81, v2
	v_mov_b32_e32 v86, v2
	v_mov_b32_e32 v87, v2
	v_mov_b32_e32 v88, v2
	v_mov_b32_e32 v89, v2
	v_mov_b32_e32 v94, v2
	v_mov_b32_e32 v95, v2
	v_mov_b32_e32 v96, v2
	v_mov_b32_e32 v97, v2
	v_mov_b32_e32 v102, v2
	v_mov_b32_e32 v103, v2
	v_mov_b32_e32 v104, v2
	v_mov_b32_e32 v105, v2
	v_mov_b32_e32 v110, v2
	v_mov_b32_e32 v111, v2
	v_mov_b32_e32 v112, v2
	v_mov_b32_e32 v113, v2
	v_mov_b32_e32 v118, v2
	v_mov_b32_e32 v119, v2
	v_mov_b32_e32 v120, v2
	v_mov_b32_e32 v121, v2
	v_mov_b32_e32 v126, v2
	v_mov_b32_e32 v127, v2
	v_mov_b32_e32 v128, v2
	v_mov_b32_e32 v129, v2
	.p2alignl 6, 3212836864

.LBB0_726:
	v_mov_b64_e32 v[152:153], v[2:3]
	v_mov_b64_e32 v[154:155], v[4:5]
	v_mov_b64_e32 v[156:157], v[30:31]
	v_mov_b64_e32 v[158:159], v[26:27]
	v_mov_b64_e32 v[160:161], v[28:29]
	v_mov_b64_e32 v[162:163], v[24:25]
	v_mov_b64_e32 v[164:165], v[12:13]
	v_mov_b64_e32 v[166:167], v[10:11]
	v_mov_b64_e32 v[168:169], v[8:9]
	v_mov_b64_e32 v[170:171], v[6:7]
	v_mov_b64_e32 v[172:173], v[14:15]
	v_mov_b64_e32 v[174:175], v[16:17]
	v_mov_b64_e32 v[176:177], v[18:19]
	v_mov_b64_e32 v[178:179], v[20:21]
	v_mov_b64_e32 v[180:181], v[22:23]
	v_mov_b64_e32 v[182:183], v[32:33]
	s_mov_b32 s6, 0x8000
	s_mov_b64 s[4:5], 0
	s_and_b64 vcc, exec, s[0:1]
	s_cbranch_vccnz .LBB0_719
	.p2alignl 6, 3212836864

.LBB0_819:
	s_ashr_i32 s37, s36, 31
	s_lshl_b64 s[22:23], s[36:37], 19
	s_add_u32 s38, s92, s22
	s_addc_u32 s39, s93, s23
	s_and_b64 s[22:23], s[40:41], exec
	s_cselect_b32 s22, s39, s11
	s_cselect_b32 s23, s38, s10
	s_ashr_i32 s9, s8, 31
	s_lshl_b64 s[24:25], s[8:9], 19
	s_add_u32 s44, s0, s24
	s_addc_u32 s45, s1, s25
	s_and_b64 s[24:25], s[40:41], exec
	s_cselect_b32 s9, s45, s43
	s_cselect_b32 s24, s44, s42
	s_add_u32 s10, s10, 0x40080
	s_addc_u32 s11, s11, 0
	s_add_u32 s25, s42, 0x100
	v_mov_b32_e32 v2, 0
	s_addc_u32 s26, s43, 0
	s_mov_b32 s27, -2
	v_mov_b32_e32 v3, v2
	v_mov_b32_e32 v4, v2
	v_mov_b32_e32 v5, v2
	v_mov_b32_e32 v6, v2
	v_mov_b32_e32 v7, v2
	v_mov_b32_e32 v8, v2
	v_mov_b32_e32 v9, v2
	v_mov_b32_e32 v18, v2
	v_mov_b32_e32 v19, v2
	v_mov_b32_e32 v20, v2
	v_mov_b32_e32 v21, v2
	v_mov_b32_e32 v22, v2
	v_mov_b32_e32 v23, v2
	v_mov_b32_e32 v24, v2
	v_mov_b32_e32 v25, v2
	v_mov_b32_e32 v34, v2
	v_mov_b32_e32 v35, v2
	v_mov_b32_e32 v36, v2
	v_mov_b32_e32 v37, v2
	v_mov_b32_e32 v38, v2
	v_mov_b32_e32 v39, v2
	v_mov_b32_e32 v40, v2
	v_mov_b32_e32 v41, v2
	v_mov_b32_e32 v50, v2
	v_mov_b32_e32 v51, v2
	v_mov_b32_e32 v52, v2
	v_mov_b32_e32 v53, v2
	v_mov_b32_e32 v54, v2
	v_mov_b32_e32 v55, v2
	v_mov_b32_e32 v56, v2
	v_mov_b32_e32 v57, v2
	v_mov_b32_e32 v10, v2
	v_mov_b32_e32 v11, v2
	v_mov_b32_e32 v12, v2
	v_mov_b32_e32 v13, v2
	v_mov_b32_e32 v14, v2
	v_mov_b32_e32 v15, v2
	v_mov_b32_e32 v16, v2
	v_mov_b32_e32 v17, v2
	v_mov_b32_e32 v26, v2
	v_mov_b32_e32 v27, v2
	v_mov_b32_e32 v28, v2
	v_mov_b32_e32 v29, v2
	v_mov_b32_e32 v30, v2
	v_mov_b32_e32 v31, v2
	v_mov_b32_e32 v32, v2
	v_mov_b32_e32 v33, v2
	v_mov_b32_e32 v42, v2
	v_mov_b32_e32 v43, v2
	v_mov_b32_e32 v44, v2
	v_mov_b32_e32 v45, v2
	v_mov_b32_e32 v46, v2
	v_mov_b32_e32 v47, v2
	v_mov_b32_e32 v48, v2
	v_mov_b32_e32 v49, v2
	v_mov_b32_e32 v58, v2
	v_mov_b32_e32 v59, v2
	v_mov_b32_e32 v60, v2
	v_mov_b32_e32 v61, v2
	v_mov_b32_e32 v62, v2
	v_mov_b32_e32 v63, v2
	v_mov_b32_e32 v64, v2
	v_mov_b32_e32 v65, v2
	v_mov_b32_e32 v66, v2
	v_mov_b32_e32 v67, v2
	v_mov_b32_e32 v68, v2
	v_mov_b32_e32 v69, v2
	v_mov_b32_e32 v70, v2
	v_mov_b32_e32 v71, v2
	v_mov_b32_e32 v72, v2
	v_mov_b32_e32 v73, v2
	v_mov_b32_e32 v82, v2
	v_mov_b32_e32 v83, v2
	v_mov_b32_e32 v84, v2
	v_mov_b32_e32 v85, v2
	v_mov_b32_e32 v86, v2
	v_mov_b32_e32 v87, v2
	v_mov_b32_e32 v88, v2
	v_mov_b32_e32 v89, v2
	v_mov_b32_e32 v114, v2
	v_mov_b32_e32 v115, v2
	v_mov_b32_e32 v116, v2
	v_mov_b32_e32 v117, v2
	v_mov_b32_e32 v118, v2
	v_mov_b32_e32 v119, v2
	v_mov_b32_e32 v120, v2
	v_mov_b32_e32 v121, v2
	v_mov_b32_e32 v142, v2
	v_mov_b32_e32 v143, v2
	v_mov_b32_e32 v144, v2
	v_mov_b32_e32 v145, v2
	v_mov_b32_e32 v146, v2
	v_mov_b32_e32 v147, v2
	v_mov_b32_e32 v148, v2
	v_mov_b32_e32 v149, v2
	v_mov_b32_e32 v74, v2
	v_mov_b32_e32 v75, v2
	v_mov_b32_e32 v76, v2
	v_mov_b32_e32 v77, v2
	v_mov_b32_e32 v78, v2
	v_mov_b32_e32 v79, v2
	v_mov_b32_e32 v80, v2
	v_mov_b32_e32 v81, v2
	v_mov_b32_e32 v98, v2
	v_mov_b32_e32 v99, v2
	v_mov_b32_e32 v100, v2
	v_mov_b32_e32 v101, v2
	v_mov_b32_e32 v110, v2
	v_mov_b32_e32 v111, v2
	v_mov_b32_e32 v112, v2
	v_mov_b32_e32 v113, v2
	v_mov_b32_e32 v126, v2
	v_mov_b32_e32 v127, v2
	v_mov_b32_e32 v128, v2
	v_mov_b32_e32 v129, v2
	v_mov_b32_e32 v134, v2
	v_mov_b32_e32 v135, v2
	v_mov_b32_e32 v136, v2
	v_mov_b32_e32 v137, v2
	v_mov_b32_e32 v170, v2
	v_mov_b32_e32 v171, v2
	v_mov_b32_e32 v172, v2
	v_mov_b32_e32 v173, v2
	v_mov_b32_e32 v174, v2
	v_mov_b32_e32 v175, v2
	v_mov_b32_e32 v176, v2
	v_mov_b32_e32 v177, v2
	.p2alignl 6, 3212836864

.LBB0_944:
	s_ashr_i32 s41, s40, 31
	s_lshl_b64 s[22:23], s[40:41], 19
	s_add_u32 s42, s88, s22
	s_addc_u32 s43, s89, s23
	s_and_b64 s[22:23], s[36:37], exec
	s_cselect_b32 s21, s43, s11
	s_cselect_b32 s22, s42, s10
	s_ashr_i32 s39, s38, 31
	s_lshl_b64 s[24:25], s[38:39], 19
	s_add_u32 s44, s52, s24
	s_addc_u32 s45, s53, s25
	s_and_b64 s[24:25], s[36:37], exec
	s_cselect_b32 s23, s45, s49
	s_cselect_b32 s24, s44, s48
	s_add_u32 s10, s10, 0x40080
	s_addc_u32 s11, s11, 0
	s_add_u32 s25, s48, 0x100
	v_mov_b32_e32 v2, 0
	s_addc_u32 s26, s49, 0
	s_mov_b32 s27, -2
	v_mov_b32_e32 v3, v2
	v_mov_b32_e32 v4, v2
	v_mov_b32_e32 v5, v2
	v_mov_b32_e32 v6, v2
	v_mov_b32_e32 v7, v2
	v_mov_b32_e32 v8, v2
	v_mov_b32_e32 v9, v2
	v_mov_b32_e32 v18, v2
	v_mov_b32_e32 v19, v2
	v_mov_b32_e32 v20, v2
	v_mov_b32_e32 v21, v2
	v_mov_b32_e32 v22, v2
	v_mov_b32_e32 v23, v2
	v_mov_b32_e32 v24, v2
	v_mov_b32_e32 v25, v2
	v_mov_b32_e32 v34, v2
	v_mov_b32_e32 v35, v2
	v_mov_b32_e32 v36, v2
	v_mov_b32_e32 v37, v2
	v_mov_b32_e32 v38, v2
	v_mov_b32_e32 v39, v2
	v_mov_b32_e32 v40, v2
	v_mov_b32_e32 v41, v2
	v_mov_b32_e32 v50, v2
	v_mov_b32_e32 v51, v2
	v_mov_b32_e32 v52, v2
	v_mov_b32_e32 v53, v2
	v_mov_b32_e32 v54, v2
	v_mov_b32_e32 v55, v2
	v_mov_b32_e32 v56, v2
	v_mov_b32_e32 v57, v2
	v_mov_b32_e32 v10, v2
	v_mov_b32_e32 v11, v2
	v_mov_b32_e32 v12, v2
	v_mov_b32_e32 v13, v2
	v_mov_b32_e32 v14, v2
	v_mov_b32_e32 v15, v2
	v_mov_b32_e32 v16, v2
	v_mov_b32_e32 v17, v2
	v_mov_b32_e32 v26, v2
	v_mov_b32_e32 v27, v2
	v_mov_b32_e32 v28, v2
	v_mov_b32_e32 v29, v2
	v_mov_b32_e32 v30, v2
	v_mov_b32_e32 v31, v2
	v_mov_b32_e32 v32, v2
	v_mov_b32_e32 v33, v2
	v_mov_b32_e32 v42, v2
	v_mov_b32_e32 v43, v2
	v_mov_b32_e32 v44, v2
	v_mov_b32_e32 v45, v2
	v_mov_b32_e32 v46, v2
	v_mov_b32_e32 v47, v2
	v_mov_b32_e32 v48, v2
	v_mov_b32_e32 v49, v2
	v_mov_b32_e32 v58, v2
	v_mov_b32_e32 v59, v2
	v_mov_b32_e32 v60, v2
	v_mov_b32_e32 v61, v2
	v_mov_b32_e32 v62, v2
	v_mov_b32_e32 v63, v2
	v_mov_b32_e32 v64, v2
	v_mov_b32_e32 v65, v2
	v_mov_b32_e32 v66, v2
	v_mov_b32_e32 v67, v2
	v_mov_b32_e32 v68, v2
	v_mov_b32_e32 v69, v2
	v_mov_b32_e32 v70, v2
	v_mov_b32_e32 v71, v2
	v_mov_b32_e32 v72, v2
	v_mov_b32_e32 v73, v2
	v_mov_b32_e32 v82, v2
	v_mov_b32_e32 v83, v2
	v_mov_b32_e32 v84, v2
	v_mov_b32_e32 v85, v2
	v_mov_b32_e32 v86, v2
	v_mov_b32_e32 v87, v2
	v_mov_b32_e32 v88, v2
	v_mov_b32_e32 v89, v2
	v_mov_b32_e32 v98, v2
	v_mov_b32_e32 v99, v2
	v_mov_b32_e32 v100, v2
	v_mov_b32_e32 v101, v2
	v_mov_b32_e32 v102, v2
	v_mov_b32_e32 v103, v2
	v_mov_b32_e32 v104, v2
	v_mov_b32_e32 v105, v2
	v_mov_b32_e32 v114, v2
	v_mov_b32_e32 v115, v2
	v_mov_b32_e32 v116, v2
	v_mov_b32_e32 v117, v2
	v_mov_b32_e32 v118, v2
	v_mov_b32_e32 v119, v2
	v_mov_b32_e32 v120, v2
	v_mov_b32_e32 v121, v2
	v_mov_b32_e32 v74, v2
	v_mov_b32_e32 v75, v2
	v_mov_b32_e32 v76, v2
	v_mov_b32_e32 v77, v2
	v_mov_b32_e32 v78, v2
	v_mov_b32_e32 v79, v2
	v_mov_b32_e32 v80, v2
	v_mov_b32_e32 v81, v2
	v_mov_b32_e32 v90, v2
	v_mov_b32_e32 v91, v2
	v_mov_b32_e32 v92, v2
	v_mov_b32_e32 v93, v2
	v_mov_b32_e32 v94, v2
	v_mov_b32_e32 v95, v2
	v_mov_b32_e32 v96, v2
	v_mov_b32_e32 v97, v2
	v_mov_b32_e32 v106, v2
	v_mov_b32_e32 v107, v2
	v_mov_b32_e32 v108, v2
	v_mov_b32_e32 v109, v2
	v_mov_b32_e32 v110, v2
	v_mov_b32_e32 v111, v2
	v_mov_b32_e32 v112, v2
	v_mov_b32_e32 v113, v2
	v_mov_b32_e32 v130, v2
	v_mov_b32_e32 v131, v2
	v_mov_b32_e32 v132, v2
	v_mov_b32_e32 v133, v2
	v_mov_b32_e32 v150, v2
	v_mov_b32_e32 v151, v2
	v_mov_b32_e32 v152, v2
	v_mov_b32_e32 v153, v2
	.p2alignl 6, 3212836864
